# scan operands staged in LDS by LDS-DMA (shared by both virtual blocks); next-layer weight conversion moved to workgroups idle in the last GEMM round; all attention items in the scan phase
# speedup vs baseline: 1.0348x; 1.0348x over previous
.LBB0_117:
	v_readlane_b32 s4, v253, 0
	s_cmpk_lt_i32 s4, 0x80
	s_cbranch_scc1 .Lconv_ret1
	s_mov_b64 s[64:65], s[0:1]
	v_lshrrev_b32_e32 v0, 8, v154
	v_mul_u32_u24_e32 v122, 0x12000, v0
	v_mov_b32_e32 v1, v154
	s_nop 0
	v_readfirstlane_b32 s5, v1
	v_writelane_b32 v254, s4, 62
	s_lshl_b32 s6, s4, 1
	v_writelane_b32 v255, s6, 0
	v_writelane_b32 v254, s5, 63
	s_ashr_i32 s5, s5, 8
	s_add_i32 s6, s5, s6
	v_writelane_b32 v255, s5, 1
	v_writelane_b32 v254, s6, 61
	s_mov_b32 s92, 0x3
	s_mov_b32 s93, 1
	s_branch .Lconv_entry
.Lconv_back1:
	s_mov_b64 s[0:1], s[64:65]

.LBB0_242:
	v_readlane_b32 s4, v253, 0
	s_cmpk_lt_i32 s4, 0x80
	s_cbranch_scc1 .Lconv_ret2
	s_mov_b64 s[64:65], s[0:1]
	v_lshrrev_b32_e32 v0, 8, v154
	v_mul_u32_u24_e32 v122, 0x12000, v0
	v_mov_b32_e32 v1, v154
	s_nop 0
	v_readfirstlane_b32 s5, v1
	v_writelane_b32 v254, s4, 62
	s_lshl_b32 s6, s4, 1
	v_writelane_b32 v255, s6, 0
	v_writelane_b32 v254, s5, 63
	s_ashr_i32 s5, s5, 8
	s_add_i32 s6, s5, s6
	v_writelane_b32 v255, s5, 1
	v_writelane_b32 v254, s6, 61
	s_mov_b32 s92, 0x4
	s_mov_b32 s93, 2
	s_branch .Lconv_entry

.LBB0_272:
	s_or_b64 exec, exec, s[0:1]
	v_mov_b32_e32 v0, v154
	s_waitcnt lgkmcnt(0)
	s_barrier
	v_readlane_b32 s0, v253, 0
	v_lshrrev_b32_e32 v0, 8, v0
	v_mul_u32_u24_e32 v122, 0x12000, v0
	v_mov_b32_e32 v0, v154
	s_lshl_b32 s4, s0, 1
	v_readfirstlane_b32 s1, v0
	s_ashr_i32 s1, s1, 8
	s_add_i32 s26, s1, s4
	s_cmpk_gt_i32 s26, 0x7ff
	s_cbranch_scc1 .LBB0_362
	v_readlane_b32 s4, v254, 57
	s_lshl_b32 s5, s4, 6
	v_writelane_b32 v254, s5, 61
	s_lshl_b32 s4, s4, 3
	s_lshl_b32 s0, s0, 7
	s_lshl_b32 s1, s1, 6
	v_add_u32_e32 v123, 0x8800, v122
	v_add_u32_e32 v124, 0xcc00, v122
	v_add_u32_e32 v125, 0x11000, v122
	v_add_u32_e32 v126, 0x11100, v122
	v_add_u32_e32 v127, 0x11200, v122
	v_writelane_b32 v254, s4, 62
	v_add_u32_e32 v128, 0x110fc, v122
	s_add_i32 s23, s0, s1
	s_branch .LBB0_276

.LBB0_275:
	v_readlane_b32 s0, v254, 51
	s_add_i32 s26, s26, s0
	v_readlane_b32 s0, v254, 44
	s_add_i32 s23, s23, s0
	s_cmpk_gt_i32 s26, 0x7ff
	v_readlane_b32 s1, v254, 52
	s_cbranch_scc1 .LBB0_362

.LBB0_392:
	s_or_b64 exec, exec, s[0:1]
	v_mov_b32_e32 v0, v154
	s_waitcnt lgkmcnt(0)
	s_barrier
	v_readlane_b32 s0, v253, 0
	v_lshrrev_b32_e32 v0, 8, v0
	v_mul_u32_u24_e32 v122, 0x12000, v0
	v_mov_b32_e32 v0, v154
	s_nop 0
	v_writelane_b32 v254, s0, 62
	v_readfirstlane_b32 s1, v0
	s_lshl_b32 s0, s0, 1
	v_writelane_b32 v255, s0, 0
	v_writelane_b32 v254, s1, 63
	s_ashr_i32 s1, s1, 8
	s_add_i32 s0, s1, s0
	v_writelane_b32 v255, s1, 1
	v_writelane_b32 v254, s0, 61
	s_cmpk_gt_i32 s0, 0xff
	s_mov_b64 s[0:1], -1
	s_cbranch_scc0 .LBB0_465
	v_readlane_b32 s0, v254, 61
	s_cmpk_gt_u32 s0, 0x4ff
	s_cbranch_scc1 .LBB0_430
	v_readlane_b32 s0, v254, 61
	s_add_i32 s23, s0, 0xffffff00
	v_readlane_b32 s0, v254, 57
	s_lshl_b32 s12, s0, 6
	s_branch .LBB0_396

.LBB0_430:
	s_mov_b32 s92, 0x38
	s_mov_b32 s93, 0
.Lconv_entry:
	v_readlane_b32 s0, v254, 57
	s_cmp_lg_u32 s0, 3
	v_readlane_b32 s23, v254, 23
	v_readlane_b32 s26, v254, 45
	s_cbranch_scc0 .LBB0_464
	v_readlane_b32 s0, v254, 57
	s_add_i32 s14, s0, 1
	v_readlane_b32 s0, v254, 61
	s_add_i32 s12, s0, 0xffffff00
	s_bitcmp1_b32 s14, 0
	s_cselect_b32 s13, 0x3680000, 0
	s_cmpk_lt_i32 s0, 0x680
	s_mul_hi_u32 s5, s14, 0x580000
	s_mul_i32 s4, s14, 0x580000
	v_mov_b32_e32 v2, v154
	s_cselect_b64 s[8:9], -1, 0
	s_cmpk_gt_i32 s0, 0x67f
	s_movk_i32 s27, 0x5800
	s_cbranch_scc1 .LBB0_434
	v_and_b32_e32 v3, 0xff, v2
	v_bfe_u32 v4, v2, 4, 4
	v_lshlrev_b32_e32 v0, 4, v2
	v_bfe_u32 v5, v2, 3, 5
	v_lshlrev_b32_e32 v6, 3, v2
	v_lshrrev_b32_e32 v7, 2, v2
	v_lshrrev_b32_e32 v2, 5, v2
	s_add_u32 s0, s72, s13
	v_readlane_b32 s36, v253, 11
	v_and_b32_e32 v6, 56, v6
	v_and_b32_e32 v7, 24, v7
	v_and_b32_e32 v2, 4, v2
	v_bfe_u32 v3, v3, 3, 2
	s_addc_u32 s1, s73, 0
	s_lshl_b64 s[6:7], s[4:5], 2
	v_readlane_b32 s46, v253, 21
	v_or3_b32 v7, v7, v2, v3
	v_lshlrev_b32_e32 v2, 1, v6
	v_mov_b32_e32 v3, v137
	v_readlane_b32 s47, v253, 22
	s_add_u32 s6, s46, s6
	v_and_b32_e32 v136, 0xf0, v0
	v_lshl_add_u64 v[2:3], s[0:1], 0, v[2:3]
	v_mul_u32_u24_e32 v6, 0x41, v6
	v_lshlrev_b32_e32 v11, 2, v7
	v_mul_u32_u24_e32 v7, 0x104, v4
	v_readlane_b32 s0, v254, 62
	v_readlane_b32 s1, v255, 1
	s_addc_u32 s7, s47, s7
	v_lshlrev_b32_e32 v12, 2, v6
	v_add3_u32 v7, v122, v7, v136
	s_lshl_b32 s0, s0, 7
	s_lshl_b32 s1, s1, 6
	v_lshl_add_u64 v[0:1], s[6:7], 0, v[136:137]
	v_add3_u32 v6, v122, v11, v12
	v_add_u32_e32 v8, 0x1040, v7
	v_add_u32_e32 v9, 0x2080, v7
	v_add_u32_e32 v10, 0x30c0, v7
	v_add3_u32 v11, v122, v12, v11
	s_add_i32 s6, s0, s1
	s_mov_b32 s7, s12
	v_readlane_b32 s37, v253, 12
	v_readlane_b32 s38, v253, 13
	v_readlane_b32 s39, v253, 14
	v_readlane_b32 s40, v253, 15
	v_readlane_b32 s41, v253, 16
	v_readlane_b32 s42, v253, 17
	v_readlane_b32 s43, v253, 18
	v_readlane_b32 s44, v253, 19
	v_readlane_b32 s45, v253, 20
	v_readlane_b32 s48, v253, 23
	v_readlane_b32 s49, v253, 24
	v_readlane_b32 s50, v253, 25
	v_readlane_b32 s51, v253, 26
	s_bitcmp1_b32 s92, 0
	s_cbranch_scc0 .LBB0_434

.LBB0_434:
	v_readlane_b32 s0, v254, 61
	s_cmpk_lt_i32 s0, 0x3c0
	s_mov_b32 s15, s52
	s_mul_hi_u32 s7, s14, 0x2c0000
	s_mul_i32 s6, s14, 0x2c0000
	v_mov_b32_e32 v2, v154
	s_cselect_b64 s[10:11], -1, 0
	s_cmpk_gt_i32 s0, 0x3bf
	s_cbranch_scc1 .LBB0_437
	v_readlane_b32 s0, v253, 57
	v_and_b32_e32 v3, 0xff, v2
	v_bfe_u32 v4, v2, 4, 4
	v_lshlrev_b32_e32 v0, 4, v2
	v_bfe_u32 v5, v2, 3, 5
	v_lshlrev_b32_e32 v6, 3, v2
	v_lshrrev_b32_e32 v7, 2, v2
	v_lshrrev_b32_e32 v2, 5, v2
	s_add_u32 s0, s0, s13
	v_readlane_b32 s1, v253, 58
	v_readlane_b32 s36, v253, 11
	v_and_b32_e32 v6, 56, v6
	v_and_b32_e32 v7, 24, v7
	v_and_b32_e32 v2, 4, v2
	v_bfe_u32 v3, v3, 3, 2
	s_addc_u32 s1, s1, 0
	s_lshl_b64 s[26:27], s[6:7], 2
	v_readlane_b32 s48, v253, 23
	v_or3_b32 v7, v7, v2, v3
	v_lshlrev_b32_e32 v2, 1, v6
	v_mov_b32_e32 v3, v137
	v_readlane_b32 s49, v253, 24
	s_add_u32 s26, s48, s26
	v_and_b32_e32 v136, 0xf0, v0
	v_lshl_add_u64 v[2:3], s[0:1], 0, v[2:3]
	v_mul_u32_u24_e32 v6, 0x41, v6
	v_lshlrev_b32_e32 v11, 2, v7
	v_mul_u32_u24_e32 v7, 0x104, v4
	v_readlane_b32 s0, v254, 62
	v_readlane_b32 s1, v255, 1
	v_readlane_b32 s37, v253, 12
	s_addc_u32 s27, s49, s27
	v_lshlrev_b32_e32 v12, 2, v6
	v_add3_u32 v7, v122, v7, v136
	s_lshl_b32 s0, s0, 7
	s_lshl_b32 s1, s1, 6
	v_lshl_add_u64 v[0:1], s[26:27], 0, v[136:137]
	v_add3_u32 v6, v122, v11, v12
	v_add_u32_e32 v8, 0x1040, v7
	v_add_u32_e32 v9, 0x2080, v7
	v_add_u32_e32 v10, 0x30c0, v7
	v_add3_u32 v11, v122, v12, v11
	s_add_i32 s23, s0, s1
	s_mov_b32 s26, s12
	v_readlane_b32 s36, v254, 23
	v_readlane_b32 s37, v254, 45
	v_readlane_b32 s38, v253, 13
	v_readlane_b32 s39, v253, 14
	v_readlane_b32 s40, v253, 15
	v_readlane_b32 s41, v253, 16
	v_readlane_b32 s42, v253, 17
	v_readlane_b32 s43, v253, 18
	v_readlane_b32 s44, v253, 19
	v_readlane_b32 s45, v253, 20
	v_readlane_b32 s46, v253, 21
	v_readlane_b32 s47, v253, 22
	v_readlane_b32 s50, v253, 25
	v_readlane_b32 s51, v253, 26
	s_bitcmp1_b32 s92, 1
	s_cbranch_scc0 .LBB0_437

.LBB0_437:
	v_readlane_b32 s0, v254, 61
	v_mov_b32_e32 v0, v154
	s_cmpk_gt_i32 s0, 0x97f
	s_cbranch_scc1 .LBB0_449
	v_readlane_b32 s0, v253, 59
	s_add_u32 s0, s0, s13
	v_readlane_b32 s1, v253, 60
	s_addc_u32 s1, s1, 0
	s_mul_i32 s26, s14, 0x2110000
	v_readlane_b32 s36, v253, 27
	v_and_b32_e32 v1, 0xff, v0
	v_bfe_u32 v2, v0, 4, 4
	v_lshlrev_b32_e32 v3, 2, v0
	v_bfe_u32 v12, v0, 3, 5
	v_lshlrev_b32_e32 v4, 3, v0
	v_lshrrev_b32_e32 v5, 2, v0
	v_lshrrev_b32_e32 v0, 5, v0
	s_mul_hi_u32 s23, s14, 0x2110000
	v_readlane_b32 s37, v253, 28
	s_add_u32 s26, s36, s26
	v_and_b32_e32 v3, 60, v3
	v_and_b32_e32 v4, 56, v4
	v_and_b32_e32 v5, 24, v5
	v_and_b32_e32 v0, 4, v0
	v_bfe_u32 v1, v1, 3, 2
	s_addc_u32 s27, s37, s23
	v_lshlrev_b32_e32 v136, 2, v3
	v_or3_b32 v5, v5, v0, v1
	v_lshlrev_b32_e32 v0, 1, v4
	v_mov_b32_e32 v1, v137
	v_lshl_add_u64 v[8:9], s[26:27], 0, v[136:137]
	v_lshl_add_u64 v[10:11], s[0:1], 0, v[0:1]
	v_mul_u32_u24_e32 v0, 0x41, v4
	v_cmp_gt_u32_e64 s[0:1], 16, v3
	v_mul_u32_u24_e32 v3, 0x104, v2
	v_readlane_b32 s26, v254, 62
	v_lshlrev_b32_e32 v1, 2, v5
	v_lshlrev_b32_e32 v0, 2, v0
	v_add3_u32 v14, v122, v3, v136
	v_readlane_b32 s23, v255, 1
	s_lshl_b32 s26, s26, 7
	v_add3_u32 v13, v122, v1, v0
	v_add_u32_e32 v15, 0x1040, v14
	v_add_u32_e32 v16, 0x2080, v14
	v_add_u32_e32 v17, 0x30c0, v14
	v_add3_u32 v18, v122, v0, v1
	s_lshl_b32 s23, s23, 6
	v_or_b32_e32 v19, s26, v2
	s_add_i32 s53, s26, 0xffffc000
	s_mov_b32 s58, s12
	v_readlane_b32 s38, v253, 29
	v_readlane_b32 s39, v253, 30
	v_readlane_b32 s40, v253, 31
	v_readlane_b32 s41, v253, 32
	v_readlane_b32 s42, v253, 33
	v_readlane_b32 s43, v253, 34
	v_readlane_b32 s44, v253, 35
	v_readlane_b32 s45, v253, 36
	v_readlane_b32 s46, v253, 37
	v_readlane_b32 s47, v253, 38
	v_readlane_b32 s48, v253, 39
	v_readlane_b32 s49, v253, 40
	v_readlane_b32 s50, v253, 41
	v_readlane_b32 s51, v253, 42
	s_bitcmp1_b32 s92, 2
	s_cbranch_scc0 .LBB0_449
	s_branch .LBB0_440

.LBB0_449:
	s_lshl_b64 s[0:1], s[14:15], 20
	v_readlane_b32 s14, v254, 61
	v_mov_b32_e32 v2, v154
	s_cmpk_gt_i32 s14, 0x13f
	s_cbranch_scc1 .LBB0_452
	v_readlane_b32 s14, v254, 24
	v_and_b32_e32 v3, 0xff, v2
	v_bfe_u32 v4, v2, 4, 4
	v_lshlrev_b32_e32 v0, 4, v2
	v_bfe_u32 v5, v2, 3, 5
	v_lshlrev_b32_e32 v6, 3, v2
	v_lshrrev_b32_e32 v7, 2, v2
	v_lshrrev_b32_e32 v2, 5, v2
	s_add_u32 s14, s14, s13
	v_readlane_b32 s15, v254, 25
	v_readlane_b32 s36, v253, 27
	v_and_b32_e32 v6, 56, v6
	v_and_b32_e32 v7, 24, v7
	v_and_b32_e32 v2, 4, v2
	v_bfe_u32 v3, v3, 3, 2
	s_addc_u32 s15, s15, 0
	v_readlane_b32 s50, v253, 41
	v_or3_b32 v7, v7, v2, v3
	v_lshlrev_b32_e32 v2, 1, v6
	v_mov_b32_e32 v3, v137
	v_readlane_b32 s51, v253, 42
	s_add_u32 s26, s50, s0
	v_and_b32_e32 v136, 0xf0, v0
	v_lshl_add_u64 v[2:3], s[14:15], 0, v[2:3]
	v_mul_u32_u24_e32 v6, 0x41, v6
	v_lshlrev_b32_e32 v11, 2, v7
	v_mul_u32_u24_e32 v7, 0x104, v4
	v_readlane_b32 s14, v254, 62
	v_readlane_b32 s15, v255, 1
	v_readlane_b32 s37, v253, 28
	s_addc_u32 s27, s51, s1
	v_lshlrev_b32_e32 v12, 2, v6
	v_add3_u32 v7, v122, v7, v136
	s_lshl_b32 s14, s14, 7
	s_lshl_b32 s15, s15, 6
	v_lshl_add_u64 v[0:1], s[26:27], 0, v[136:137]
	v_add3_u32 v6, v122, v11, v12
	v_add_u32_e32 v8, 0x1040, v7
	v_add_u32_e32 v9, 0x2080, v7
	v_add_u32_e32 v10, 0x30c0, v7
	v_add3_u32 v11, v122, v12, v11
	s_add_i32 s23, s14, s15
	s_mov_b32 s26, s12
	v_readlane_b32 s36, v254, 23
	v_readlane_b32 s37, v254, 45
	v_readlane_b32 s38, v253, 29
	v_readlane_b32 s39, v253, 30
	v_readlane_b32 s40, v253, 31
	v_readlane_b32 s41, v253, 32
	v_readlane_b32 s42, v253, 33
	v_readlane_b32 s43, v253, 34
	v_readlane_b32 s44, v253, 35
	v_readlane_b32 s45, v253, 36
	v_readlane_b32 s46, v253, 37
	v_readlane_b32 s47, v253, 38
	v_readlane_b32 s48, v253, 39
	v_readlane_b32 s49, v253, 40
	s_bitcmp1_b32 s92, 3
	s_cbranch_scc0 .LBB0_452

.LBB0_452:
	v_readlane_b32 s23, v254, 61
	s_cmpk_lt_i32 s23, 0x200
	v_mov_b32_e32 v2, v154
	s_cselect_b64 s[14:15], -1, 0
	s_cmpk_gt_i32 s23, 0x1ff
	s_cbranch_scc1 .LBB0_455
	v_readlane_b32 s23, v254, 26
	v_and_b32_e32 v3, 0xff, v2
	v_bfe_u32 v4, v2, 4, 4
	v_lshlrev_b32_e32 v0, 4, v2
	v_bfe_u32 v5, v2, 3, 5
	v_lshlrev_b32_e32 v6, 3, v2
	v_lshrrev_b32_e32 v7, 2, v2
	v_lshrrev_b32_e32 v2, 5, v2
	s_add_u32 s26, s23, s13
	v_readlane_b32 s23, v254, 27
	v_and_b32_e32 v6, 56, v6
	v_and_b32_e32 v7, 24, v7
	v_and_b32_e32 v2, 4, v2
	v_bfe_u32 v3, v3, 3, 2
	s_addc_u32 s27, s23, 0
	s_lshl_b64 s[54:55], s[0:1], 2
	v_readlane_b32 s56, v253, 1
	v_or3_b32 v7, v7, v2, v3
	v_lshlrev_b32_e32 v2, 1, v6
	v_mov_b32_e32 v3, v137
	v_readlane_b32 s57, v253, 2
	s_add_u32 s54, s56, s54
	v_and_b32_e32 v136, 0xf0, v0
	v_lshl_add_u64 v[2:3], s[26:27], 0, v[2:3]
	v_mul_u32_u24_e32 v6, 0x41, v6
	v_lshlrev_b32_e32 v11, 2, v7
	v_mul_u32_u24_e32 v7, 0x104, v4
	v_readlane_b32 s23, v254, 62
	v_readlane_b32 s26, v255, 1
	s_addc_u32 s55, s57, s55
	v_lshlrev_b32_e32 v12, 2, v6
	v_add3_u32 v7, v122, v7, v136
	s_lshl_b32 s23, s23, 7
	s_lshl_b32 s26, s26, 6
	v_lshl_add_u64 v[0:1], s[54:55], 0, v[136:137]
	v_add3_u32 v6, v122, v11, v12
	v_add_u32_e32 v8, 0x1040, v7
	v_add_u32_e32 v9, 0x2080, v7
	v_add_u32_e32 v10, 0x30c0, v7
	v_add3_u32 v11, v122, v12, v11
	s_add_i32 s23, s23, s26
	s_mov_b32 s53, s12
	v_readlane_b32 s36, v254, 23
	v_readlane_b32 s37, v254, 45
	v_readlane_b32 s58, v253, 3
	v_readlane_b32 s59, v253, 4
	v_readlane_b32 s60, v253, 5
	v_readlane_b32 s61, v253, 6
	v_readlane_b32 s62, v253, 7
	v_readlane_b32 s63, v253, 8
	s_bitcmp1_b32 s92, 4
	s_cbranch_scc0 .LBB0_455

.LBB0_455:
	v_mov_b32_e32 v2, v154
	s_andn2_b64 vcc, exec, s[14:15]
	s_cbranch_vccnz .LBB0_458
	v_readlane_b32 s14, v254, 28
	s_add_u32 s14, s14, s13
	v_readlane_b32 s15, v254, 29
	v_readlane_b32 s56, v253, 1
	s_addc_u32 s15, s15, 0
	s_lshl_b64 s[0:1], s[0:1], 2
	v_readlane_b32 s58, v253, 3
	v_and_b32_e32 v3, 0xff, v2
	v_bfe_u32 v4, v2, 4, 4
	v_lshlrev_b32_e32 v0, 4, v2
	v_bfe_u32 v5, v2, 3, 5
	v_lshlrev_b32_e32 v6, 3, v2
	v_lshrrev_b32_e32 v7, 2, v2
	v_lshrrev_b32_e32 v2, 5, v2
	v_readlane_b32 s59, v253, 4
	s_add_u32 s0, s58, s0
	v_and_b32_e32 v7, 24, v7
	v_and_b32_e32 v2, 4, v2
	v_bfe_u32 v3, v3, 3, 2
	s_addc_u32 s1, s59, s1
	v_and_b32_e32 v136, 0xf0, v0
	v_and_b32_e32 v6, 56, v6
	v_or3_b32 v7, v7, v2, v3
	v_lshl_add_u64 v[0:1], s[0:1], 0, v[136:137]
	v_lshlrev_b32_e32 v2, 1, v6
	v_mul_u32_u24_e32 v6, 0x41, v6
	v_lshlrev_b32_e32 v11, 2, v7
	v_mul_u32_u24_e32 v7, 0x104, v4
	v_readlane_b32 s0, v254, 62
	v_readlane_b32 s1, v255, 1
	v_mov_b32_e32 v3, v137
	v_lshlrev_b32_e32 v12, 2, v6
	v_add3_u32 v7, v122, v7, v136
	s_lshl_b32 s0, s0, 7
	s_lshl_b32 s1, s1, 6
	v_lshl_add_u64 v[2:3], s[14:15], 0, v[2:3]
	v_add3_u32 v6, v122, v11, v12
	v_add_u32_e32 v8, 0x1040, v7
	v_add_u32_e32 v9, 0x2080, v7
	v_add_u32_e32 v10, 0x30c0, v7
	v_add3_u32 v11, v122, v12, v11
	s_add_i32 s14, s0, s1
	s_mov_b32 s15, s12
	v_readlane_b32 s26, v254, 23
	v_readlane_b32 s27, v254, 45
	v_readlane_b32 s57, v253, 2
	v_readlane_b32 s60, v253, 5
	v_readlane_b32 s61, v253, 6
	v_readlane_b32 s62, v253, 7
	v_readlane_b32 s63, v253, 8
	s_bitcmp1_b32 s92, 5
	s_cbranch_scc0 .LBB0_458

.LBB0_458:
	v_mov_b32_e32 v2, v154
	s_andn2_b64 vcc, exec, s[8:9]
	s_cbranch_vccnz .LBB0_461
	v_readlane_b32 s0, v254, 30
	v_and_b32_e32 v3, 0xff, v2
	v_bfe_u32 v4, v2, 4, 4
	v_lshlrev_b32_e32 v0, 4, v2
	v_bfe_u32 v5, v2, 3, 5
	v_lshlrev_b32_e32 v6, 3, v2
	v_lshrrev_b32_e32 v7, 2, v2
	v_lshrrev_b32_e32 v2, 5, v2
	s_add_u32 s0, s0, s13
	v_readlane_b32 s1, v254, 31
	v_readlane_b32 s56, v253, 1
	v_and_b32_e32 v6, 56, v6
	v_and_b32_e32 v7, 24, v7
	v_and_b32_e32 v2, 4, v2
	v_bfe_u32 v3, v3, 3, 2
	s_addc_u32 s1, s1, 0
	s_lshl_b64 s[4:5], s[4:5], 2
	v_readlane_b32 s62, v253, 7
	v_or3_b32 v7, v7, v2, v3
	v_lshlrev_b32_e32 v2, 1, v6
	v_mov_b32_e32 v3, v137
	v_readlane_b32 s63, v253, 8
	s_add_u32 s4, s62, s4
	v_and_b32_e32 v136, 0xf0, v0
	v_lshl_add_u64 v[2:3], s[0:1], 0, v[2:3]
	v_mul_u32_u24_e32 v6, 0x41, v6
	v_lshlrev_b32_e32 v11, 2, v7
	v_mul_u32_u24_e32 v7, 0x104, v4
	v_readlane_b32 s0, v254, 62
	v_readlane_b32 s1, v255, 1
	s_addc_u32 s5, s63, s5
	v_lshlrev_b32_e32 v12, 2, v6
	v_add3_u32 v7, v122, v7, v136
	s_lshl_b32 s0, s0, 7
	s_lshl_b32 s1, s1, 6
	v_lshl_add_u64 v[0:1], s[4:5], 0, v[136:137]
	v_add3_u32 v6, v122, v11, v12
	v_add_u32_e32 v8, 0x1040, v7
	v_add_u32_e32 v9, 0x2080, v7
	v_add_u32_e32 v10, 0x30c0, v7
	v_add3_u32 v11, v122, v12, v11
	s_add_i32 s4, s0, s1
	s_mov_b32 s5, s12
	v_readlane_b32 s15, v254, 23
	v_readlane_b32 s23, v254, 45
	s_movk_i32 s26, 0x5800
	v_readlane_b32 s57, v253, 2
	v_readlane_b32 s58, v253, 3
	v_readlane_b32 s59, v253, 4
	v_readlane_b32 s60, v253, 5
	v_readlane_b32 s61, v253, 6
	s_bitcmp1_b32 s92, 6
	s_cbranch_scc0 .LBB0_461

.LBB0_461:
	v_mov_b32_e32 v2, v154
	s_andn2_b64 vcc, exec, s[10:11]
	v_readlane_b32 s8, v254, 23
	v_readlane_b32 s9, v254, 45
	s_cbranch_vccnz .LBB0_464
	v_readlane_b32 s0, v254, 32
	v_and_b32_e32 v3, 0xff, v2
	v_bfe_u32 v4, v2, 4, 4
	v_lshlrev_b32_e32 v0, 4, v2
	v_bfe_u32 v5, v2, 3, 5
	v_lshlrev_b32_e32 v6, 3, v2
	v_lshrrev_b32_e32 v7, 2, v2
	v_lshrrev_b32_e32 v2, 5, v2
	s_add_u32 s0, s0, s13
	v_readlane_b32 s1, v254, 33
	v_and_b32_e32 v6, 56, v6
	v_and_b32_e32 v7, 24, v7
	v_and_b32_e32 v2, 4, v2
	v_bfe_u32 v3, v3, 3, 2
	s_addc_u32 s1, s1, 0
	s_lshl_b64 s[4:5], s[6:7], 2
	v_or3_b32 v7, v7, v2, v3
	v_lshlrev_b32_e32 v2, 1, v6
	v_mov_b32_e32 v3, v137
	s_add_u32 s4, s68, s4
	v_and_b32_e32 v136, 0xf0, v0
	v_lshl_add_u64 v[2:3], s[0:1], 0, v[2:3]
	v_mul_u32_u24_e32 v6, 0x41, v6
	v_lshlrev_b32_e32 v11, 2, v7
	v_mul_u32_u24_e32 v7, 0x104, v4
	v_readlane_b32 s0, v254, 62
	v_readlane_b32 s1, v255, 1
	s_addc_u32 s5, s69, s5
	v_lshlrev_b32_e32 v12, 2, v6
	v_add3_u32 v7, v122, v7, v136
	s_lshl_b32 s0, s0, 7
	s_lshl_b32 s1, s1, 6
	v_lshl_add_u64 v[0:1], s[4:5], 0, v[136:137]
	v_add3_u32 v6, v122, v11, v12
	v_add_u32_e32 v8, 0x1040, v7
	v_add_u32_e32 v9, 0x2080, v7
	v_add_u32_e32 v10, 0x30c0, v7
	v_add3_u32 v11, v122, v12, v11
	s_add_i32 s4, s0, s1
	s_bitcmp1_b32 s92, 7
	s_cbranch_scc0 .LBB0_464

.LBB0_464:
	s_cmp_eq_u32 s93, 1
	s_cbranch_scc1 .Lconv_back1
	s_cmp_eq_u32 s93, 2
	s_cbranch_scc1 .Lconv_back2
	s_cmp_eq_u32 s93, 3
	s_cbranch_scc1 .Lconv_back3
	s_mov_b64 s[0:1], 0

.LBB0_467:
	v_add_u32_e32 v1, 0x100, v1
	s_movk_i32 s4, 0xfff
	v_cmp_lt_u32_e32 vcc, s4, v1
	ds_write_b16 v0, v137
	s_or_b64 s[0:1], vcc, s[0:1]
	v_add_u32_e32 v0, 0x200, v0
	s_andn2_b64 exec, exec, s[0:1]
	s_cbranch_execnz .LBB0_467
	s_or_b64 exec, exec, s[0:1]
	v_readlane_b32 s1, v254, 61
	s_ashr_i32 s0, s1, 2
	v_readlane_b32 s4, v254, 63
	s_lshr_b32 s11, s4, 8
	s_ashr_i32 s4, s1, 5
	s_and_b32 s10, s1, 3
	s_ashr_i32 s1, s0, 31
	s_lshl_b64 s[8:9], s[0:1], 18
	s_lshl_b64 s[6:7], s[0:1], 19
	v_readlane_b32 s12, v254, 21
	v_and_b32_e32 v74, 15, v36
	v_readlane_b32 s13, v254, 22
	s_add_u32 s12, s12, s6
	v_lshrrev_b32_e32 v72, 6, v37
	s_addc_u32 s13, s13, s7
	v_readlane_b32 s14, v254, 13
	v_lshlrev_b32_e32 v75, 7, v74
	v_readlane_b32 s15, v254, 14
	s_add_u32 s14, s14, s6
	v_lshl_or_b32 v136, v72, 11, v75
	s_addc_u32 s15, s15, s7
	v_lshlrev_b32_e32 v38, 1, v136
	v_mov_b32_e32 v39, v137
	v_readlane_b32 s5, v254, 17
	v_bfe_u32 v73, v36, 4, 2
	v_lshl_add_u64 v[0:1], s[12:13], 0, v[38:39]
	s_add_u32 s12, s5, s8
	v_readlane_b32 s5, v254, 18
	v_lshlrev_b32_e32 v58, 4, v73
	v_mov_b32_e32 v59, v137
	s_addc_u32 s13, s5, s9
	v_readlane_b32 s5, v254, 15
	v_lshl_add_u64 v[0:1], v[0:1], 0, v[58:59]
	v_lshl_add_u64 v[2:3], s[14:15], 0, v[38:39]
	s_add_u32 s14, s5, s6
	v_readlane_b32 s5, v254, 16
	s_waitcnt lgkmcnt(0)
	s_barrier
	v_lshl_add_u64 v[2:3], v[2:3], 0, v[58:59]
	s_nop 0
	s_nop 0
	s_nop 0
	s_nop 0
	s_nop 0
	s_nop 0
	s_nop 0
	s_nop 0
	s_addc_u32 s15, s5, s7
	v_lshl_add_u64 v[0:1], s[12:13], 0, v[136:137]
	v_readlane_b32 s12, v254, 19
	v_lshl_add_u64 v[2:3], s[14:15], 0, v[58:59]
	v_lshl_or_b32 v60, v72, 12, v75
	v_mov_b32_e32 v61, v137
	v_readlane_b32 s13, v254, 20
	s_add_u32 s12, s12, s6
	v_lshl_add_u64 v[0:1], v[0:1], 0, v[58:59]
	v_lshl_add_u64 v[2:3], v[2:3], 0, v[60:61]
	s_addc_u32 s13, s13, s7
	v_lshlrev_b32_e32 v62, 5, v72
	v_mov_b32_e32 v63, v137
	v_lshlrev_b32_e32 v56, 3, v73
	v_mov_b32_e32 v57, v137
	global_load_dwordx4 v[16:19], v[0:1], off
	global_load_dwordx4 v[20:23], v[0:1], off offset:64
	s_nop 0
	s_nop 0
	s_nop 0
	s_nop 0
	s_nop 0
	v_lshl_add_u64 v[68:69], s[12:13], 0, v[62:63]
	v_lshl_add_u64 v[68:69], v[68:69], 0, v[56:57]
	v_lshl_or_b32 v70, s10, 12, v75
	v_mov_b32_e32 v71, v137
	s_lshl_b64 s[12:13], s[0:1], 7
	v_readlane_b32 s1, v254, 11
	v_lshl_add_u64 v[68:69], v[68:69], 0, v[70:71]
	s_add_u32 s14, s1, s12
	v_readlane_b32 s1, v254, 12
	s_addc_u32 s15, s1, s13
	global_load_dwordx2 v[104:105], v[68:69], off
	global_load_dwordx2 v[102:103], v[68:69], off offset:2048
	global_load_dword v100, v137, s[14:15]
	v_lshrrev_b32_e32 v98, 2, v37
	v_lshlrev_b32_e32 v37, 3, v37
	v_and_b32_e32 v37, 24, v37
	s_ashr_i32 s5, s4, 31
	v_and_b32_e32 v59, 0xc0, v36
	v_lshlrev_b32_e32 v96, 1, v37
	v_mul_u32_u24_e32 v37, 0x88, v74
	s_lshl_b64 s[4:5], s[4:5], 22
	v_add_u32_e32 v61, v122, v59
	v_lshlrev_b32_e32 v37, 1, v37
	s_add_u32 s1, s4, 0x24500000
	v_add3_u32 v124, v122, v58, v37
	v_add3_u32 v99, v61, v56, v37
	v_lshl_or_b32 v37, v98, 11, s1
	v_readlane_b32 s1, v255, 0
	s_addc_u32 s14, s5, 0
	s_lshl_b32 s0, s0, 8
	s_add_i32 s1, s1, s11
	s_and_b32 s0, s0, 0x700
	s_and_b32 s1, s1, 3
	v_and_b32_e32 v36, 3, v36
	v_add_u32_e32 v57, v122, v62
	v_mul_u32_u24_e32 v62, 0x50, v98
	v_or_b32_e32 v37, s0, v37
	s_lshl_b32 s1, s1, 6
	v_lshlrev_b32_e32 v36, 4, v36
	v_lshlrev_b32_e32 v39, 2, v73
	v_add3_u32 v97, v122, v62, v96
	v_mul_u32_u24_e32 v62, 0x48, v74
	v_or3_b32 v106, v37, s1, v36
	s_add_u32 s1, s12, 0x267e0004
	v_lshl_or_b32 v39, v72, 4, v39
	v_lshlrev_b32_e32 v62, 1, v62
	s_addc_u32 s11, s13, 0
	v_lshrrev_b32_e32 v36, 1, v59
	v_add3_u32 v117, v57, v56, v62
	v_or_b32_e32 v62, 0x800, v75
	v_mul_u32_u24_e32 v39, 40, v39
	v_or_b32_e32 v36, s6, v36
	v_or3_b32 v110, s8, v58, v136
	s_add_u32 s8, s6, 0x21504800
	v_sub_u32_e32 v57, 0, v75
	v_sub_u32_e32 v62, 0, v62
	v_lshlrev_b32_e32 v63, 1, v74
	v_lshlrev_b32_e32 v39, 1, v39
	v_or3_b32 v108, v36, v56, v70
	v_mov_b32_e32 v109, s7
	s_addc_u32 s7, s7, 0
	v_mov_b32_e32 v36, 0
	v_add3_u32 v101, v122, v63, v39
	v_mov_b32_e32 v107, s14
	v_mov_b32_e32 v111, s9
	v_or3_b32 v112, s8, v58, v60
	v_mov_b32_e32 v113, s7
	v_or3_b32 v114, s6, v58, v38
	v_mov_b32_e32 v115, v109
	s_mov_b32 s6, 30
	v_add_u32_e32 v122, v124, v57
	v_add_u32_e32 v123, v124, v62
	v_mov_b32_e32 v37, v36
	v_mov_b32_e32 v38, v36
	v_mov_b32_e32 v39, v36
	v_mov_b32_e32 v56, v36
	v_mov_b32_e32 v57, v36
	v_mov_b32_e32 v58, v36
	v_mov_b32_e32 v59, v36
	v_mov_b32_e32 v60, v36
	v_mov_b32_e32 v61, v36
	v_mov_b32_e32 v62, v36
	v_mov_b32_e32 v63, v36
	v_mov_b32_e32 v68, v36
	v_mov_b32_e32 v69, v36
	v_mov_b32_e32 v70, v36
	v_mov_b32_e32 v71, v36
	s_mov_b64 s[12:13], 0x20000
	s_mov_b64 s[14:15], 0x2000
	s_mov_b64 s[26:27], 0x4000
	v_lshrrev_b32_e32 v212, 6, v154
	v_and_b32_e32 v213, 63, v154
	v_lshrrev_b32_e32 v214, 4, v213
	v_lshl_add_u32 v215, v212, 3, v214
	v_xor_b32_e32 v216, v213, v215
	v_and_b32_e32 v216, 15, v216
	v_lshlrev_b32_e32 v217, 8, v215
	v_lshl_or_b32 v194, v216, 4, v217
	v_add_u32_e32 v196, 0x4000000, v194
	v_add_u32_e32 v215, 4, v215
	v_xor_b32_e32 v216, v213, v215
	v_and_b32_e32 v216, 15, v216
	v_lshlrev_b32_e32 v217, 8, v215
	v_lshl_or_b32 v195, v216, 4, v217
	v_add_u32_e32 v197, 0x4000000, v195
	v_lshrrev_b32_e32 v214, 3, v213
	v_lshl_add_u32 v215, v212, 4, v214
	v_lshrrev_b32_e32 v216, 1, v215
	v_xor_b32_e32 v216, v213, v216
	v_and_b32_e32 v216, 7, v216
	v_lshlrev_b32_e32 v217, 7, v215
	v_lshl_or_b32 v217, v216, 4, v217
	v_add_u32_e32 v198, 0x6000000, v217
	v_add_u32_e32 v215, 8, v215
	v_lshrrev_b32_e32 v216, 1, v215
	v_xor_b32_e32 v216, v213, v216
	v_and_b32_e32 v216, 7, v216
	v_lshlrev_b32_e32 v217, 7, v215
	v_lshl_or_b32 v217, v216, 4, v217
	v_add_u32_e32 v199, 0x6000000, v217
	v_bfe_u32 v212, v154, 6, 2
	v_and_b32_e32 v213, 15, v154
	v_bfe_u32 v214, v154, 4, 2
	v_lshl_add_u32 v215, v212, 4, v213
	v_lshlrev_b32_e32 v215, 8, v215
	v_or_b32_e32 v216, 0, v214
	v_xor_b32_e32 v216, v216, v213
	v_and_b32_e32 v216, 15, v216
	v_lshl_or_b32 v216, v216, 4, v215
	v_add_u32_e32 v200, 0x4800, v216
	v_add_u32_e32 v204, 0x16800, v216
	v_or_b32_e32 v216, 4, v214
	v_xor_b32_e32 v216, v216, v213
	v_and_b32_e32 v216, 15, v216
	v_lshl_or_b32 v216, v216, 4, v215
	v_add_u32_e32 v201, 0x4800, v216
	v_add_u32_e32 v205, 0x16800, v216
	v_or_b32_e32 v216, 8, v214
	v_xor_b32_e32 v216, v216, v213
	v_and_b32_e32 v216, 15, v216
	v_lshl_or_b32 v216, v216, 4, v215
	v_add_u32_e32 v202, 0x4800, v216
	v_add_u32_e32 v206, 0x16800, v216
	v_or_b32_e32 v216, 12, v214
	v_xor_b32_e32 v216, v216, v213
	v_and_b32_e32 v216, 15, v216
	v_lshl_or_b32 v216, v216, 4, v215
	v_add_u32_e32 v203, 0x4800, v216
	v_add_u32_e32 v207, 0x16800, v216
	v_lshl_add_u32 v215, v212, 5, v213
	v_lshlrev_b32_e32 v215, 7, v215
	v_lshrrev_b32_e32 v217, 1, v213
	v_or_b32_e32 v216, 0, v214
	v_xor_b32_e32 v216, v216, v217
	v_and_b32_e32 v216, 7, v216
	v_lshl_or_b32 v216, v216, 4, v215
	v_add_u32_e32 v208, 0x4800, v216
	v_add_u32_e32 v210, 0x16800, v216
	v_or_b32_e32 v216, 4, v214
	v_xor_b32_e32 v216, v216, v217
	v_and_b32_e32 v216, 7, v216
	v_lshl_or_b32 v216, v216, 4, v215
	v_add_u32_e32 v209, 0x4800, v216
	v_add_u32_e32 v211, 0x16800, v216
	v_lshrrev_b32_e32 v212, 6, v154
	s_nop 0
	v_readfirstlane_b32 s36, v212
	s_lshl_b32 s36, s36, 11
	v_readlane_b32 s38, v254, 61
	s_ashr_i32 s38, s38, 2
	s_mov_b32 s39, 0
	s_lshl_b64 s[38:39], s[38:39], 19
	s_add_u32 s38, s38, s72
	s_addc_u32 s39, s39, s73
	s_add_u32 s38, s38, 0x1b500000
	s_addc_u32 s39, s39, 0
	s_add_u32 m0, s36, 0x4800
	s_nop 0
	global_load_lds_dwordx4 v194, s[38:39]
	s_add_u32 m0, s36, 0x4c00
	s_nop 0
	global_load_lds_dwordx4 v195, s[38:39]
	s_add_u32 m0, s36, 0x8800
	s_nop 0
	global_load_lds_dwordx4 v196, s[38:39]
	s_add_u32 m0, s36, 0x8c00
	s_nop 0
	global_load_lds_dwordx4 v197, s[38:39]
	s_add_u32 m0, s36, 0xc800
	s_nop 0
	global_load_lds_dwordx4 v198, s[38:39]
	s_add_u32 m0, s36, 0xcc00
	s_nop 0
	global_load_lds_dwordx4 v199, s[38:39]
	s_add_u32 s38, s38, 0x4000
	s_addc_u32 s39, s39, 0
	s_waitcnt vmcnt(0)
	s_barrier
.LBB0_469:
	s_waitcnt vmcnt(1)
	v_mov_b64_e32 v[92:93], v[16:17]
	v_mov_b64_e32 v[94:95], v[18:19]
	v_mov_b64_e32 v[88:89], v[20:21]
	v_mov_b64_e32 v[90:91], v[22:23]
	v_mov_b64_e32 v[120:121], v[104:105]
	v_mov_b64_e32 v[118:119], v[102:103]
	v_mov_b32_e32 v116, v100
	ds_read_b128 v[148:151], v200
	ds_read_b128 v[126:129], v200 offset:16384
	ds_read_b128 v[170:173], v201
	ds_read_b128 v[130:133], v201 offset:16384
	ds_read_b128 v[174:177], v202
	ds_read_b128 v[140:143], v202 offset:16384
	ds_read_b128 v[178:181], v203
	ds_read_b128 v[144:147], v203 offset:16384
	ds_read_b128 v[84:87], v208 offset:32768
	ds_read_b128 v[80:83], v208 offset:34816
	ds_read_b128 v[76:79], v209 offset:32768
	ds_read_b128 v[72:75], v209 offset:34816
	s_add_u32 m0, s36, 0x16800
	s_nop 0
	global_load_lds_dwordx4 v194, s[38:39]
	s_add_u32 m0, s36, 0x16c00
	s_nop 0
	global_load_lds_dwordx4 v195, s[38:39]
	s_add_u32 m0, s36, 0x1a800
	s_nop 0
	global_load_lds_dwordx4 v196, s[38:39]
	s_add_u32 m0, s36, 0x1ac00
	s_nop 0
	global_load_lds_dwordx4 v197, s[38:39]
	s_add_u32 m0, s36, 0x1e800
	s_nop 0
	global_load_lds_dwordx4 v198, s[38:39]
	s_add_u32 m0, s36, 0x1ec00
	s_nop 0
	global_load_lds_dwordx4 v199, s[38:39]
	s_add_u32 s38, s38, 0x4000
	s_addc_u32 s39, s39, 0
	v_lshl_add_u64 v[0:1], s[72:73], 0, v[110:111]
	s_mov_b32 s7, 0x23502000
	v_add_co_u32_e32 v0, vcc, s7, v0
	s_nop 1
	v_addc_co_u32_e32 v1, vcc, 0, v1, vcc
	global_load_dwordx4 v[16:19], v[0:1], off
	global_load_dwordx4 v[20:23], v[0:1], off offset:64
	v_lshl_add_u64 v[102:103], s[72:73], 0, v[108:109]
	s_mov_b32 s7, 0x1d504000
	v_add_co_u32_e32 v102, vcc, s7, v102
	s_add_u32 s8, s72, s1
	s_nop 0
	v_addc_co_u32_e32 v103, vcc, 0, v103, vcc
	s_addc_u32 s9, s73, s11
	global_load_dwordx2 v[104:105], v[102:103], off
	s_nop 0
	global_load_dwordx2 v[102:103], v[102:103], off offset:2048
	ds_read_b128 v[182:185], v124
	ds_read_b128 v[190:193], v124 offset:4352
	global_load_dword v100, v137, s[8:9]
	s_waitcnt lgkmcnt(1)
	v_mfma_f32_16x16x32_bf16 v[186:189], v[148:151], v[182:185], 0
	v_lshlrev_b32_e32 v134, 16, v120
	v_and_b32_e32 v135, 0xffff0000, v120
	v_lshlrev_b32_e32 v120, 16, v121
	v_mfma_f32_16x16x32_bf16 v[182:185], v[126:129], v[182:185], 0
	v_and_b32_e32 v121, 0xffff0000, v121
	v_pk_mul_f32 v[70:71], v[70:71], v[116:117] op_sel_hi:[1,0]
	v_pk_mul_f32 v[68:69], v[68:69], v[116:117] op_sel_hi:[1,0]
	s_waitcnt lgkmcnt(0)
	v_mfma_f32_16x16x32_bf16 v[148:151], v[148:151], v[190:193], 0
	v_mul_f32_e64 v58, v58, v116
	v_mul_f32_e64 v59, v59, v116
	v_pk_mul_f32 v[56:57], v[56:57], v[116:117] op_sel_hi:[1,0]
	v_pk_mul_f32 v[62:63], v[62:63], v[116:117] op_sel_hi:[1,0]
	v_mfma_f32_16x16x32_bf16 v[126:129], v[126:129], v[190:193], 0
	ds_read_b128 v[190:193], v124 offset:64
	v_pk_mul_f32 v[60:61], v[60:61], v[116:117] op_sel_hi:[1,0]
	v_pk_mul_f32 v[38:39], v[38:39], v[116:117] op_sel_hi:[1,0]
	s_waitcnt lgkmcnt(0)
	v_mfma_f32_16x16x32_bf16 v[186:189], v[170:173], v[190:193], v[186:189]
	v_mul_f32_e64 v36, v36, v116
	v_mul_f32_e64 v37, v37, v116
	s_add_i32 s6, s6, -1
	s_add_u32 s1, s1, 4
	v_mfma_f32_16x16x32_bf16 v[182:185], v[130:133], v[190:193], v[182:185]
	ds_read_b128 v[190:193], v124 offset:4416
	s_addc_u32 s11, s11, 0
	v_lshl_add_u64 v[108:109], v[108:109], 0, s[26:27]
	s_waitcnt lgkmcnt(0)
	v_mfma_f32_16x16x32_bf16 v[126:129], v[130:133], v[190:193], v[126:129]
	ds_read_b128 v[130:133], v124 offset:128
	v_lshl_add_u64 v[110:111], v[110:111], 0, s[14:15]
	v_lshl_add_u64 v[112:113], v[112:113], 0, s[26:27]
	v_mfma_f32_16x16x32_bf16 v[148:151], v[170:173], v[190:193], v[148:151]
	v_lshl_add_u64 v[114:115], v[114:115], 0, s[26:27]
	s_cmp_lg_u32 s6, 0
	s_waitcnt lgkmcnt(0)
	v_mfma_f32_16x16x32_bf16 v[170:173], v[174:177], v[130:133], v[186:189]
	v_mfma_f32_16x16x32_bf16 v[130:133], v[140:143], v[130:133], v[182:185]
	s_nop 2
	ds_read_b128 v[182:185], v124 offset:4480
	s_waitcnt lgkmcnt(0)
	v_mfma_f32_16x16x32_bf16 v[126:129], v[140:143], v[182:185], v[126:129]
	ds_read_b128 v[140:143], v124 offset:192
	s_waitcnt lgkmcnt(0)
	v_mfma_f32_16x16x32_bf16 v[170:173], v[178:181], v[140:143], v[170:173]
	v_mfma_f32_16x16x32_bf16 v[130:133], v[144:147], v[140:143], v[130:133]
	ds_read_b128 v[140:143], v124 offset:4544
	s_nop 5
	v_pk_add_f32 v[134:135], v[134:135], v[170:171] neg_lo:[0,1] neg_hi:[0,1]
	v_pk_add_f32 v[120:121], v[120:121], v[172:173] neg_lo:[0,1] neg_hi:[0,1]
	v_mfma_f32_16x16x32_bf16 v[148:151], v[174:177], v[182:185], v[148:151]
	v_cvt_pk_bf16_f32 v134, v134, v135
	v_cvt_pk_bf16_f32 v135, v120, v121
	v_lshlrev_b32_e32 v120, 16, v118
	s_waitcnt lgkmcnt(0)
	v_mfma_f32_16x16x32_bf16 v[148:151], v[178:181], v[140:143], v[148:151]
	v_and_b32_e32 v121, 0xffff0000, v118
	v_lshlrev_b32_e32 v118, 16, v119
	v_and_b32_e32 v119, 0xffff0000, v119
	ds_write_b64 v117, v[134:135] offset:8704
	v_mfma_f32_16x16x32_bf16 v[126:129], v[144:147], v[140:143], v[126:129]
	s_nop 2
	v_add_f32_e64 v120, v120, -v148
	v_add_f32_e64 v121, v121, -v149
	v_pk_add_f32 v[118:119], v[118:119], v[150:151] neg_lo:[0,1] neg_hi:[0,1]
	v_cvt_pk_bf16_f32 v120, v120, v121
	v_cvt_pk_bf16_f32 v121, v118, v119
	ds_write_b64 v117, v[120:121] offset:11008
	s_waitcnt lgkmcnt(0)
	s_barrier
	ds_read_b128 v[118:121], v122 offset:8704
	ds_read_b128 v[140:143], v123 offset:13056
	ds_read_b128 v[144:147], v122 offset:8768
	ds_read_b128 v[148:151], v123 offset:13120
	s_waitcnt lgkmcnt(3)
	v_mfma_f32_16x16x32_bf16 v[130:133], v[92:95], v[118:121], v[130:133]
	s_waitcnt lgkmcnt(2)
	v_mfma_f32_16x16x32_bf16 v[92:95], v[92:95], v[140:143], v[126:129]
	v_mfma_f32_16x16x32_bf16 v[68:71], v[84:87], v[118:121], v[68:71]
	v_mfma_f32_16x16x32_bf16 v[56:59], v[80:83], v[118:121], v[56:59]
	s_waitcnt lgkmcnt(1)
	v_mfma_f32_16x16x32_bf16 v[126:129], v[88:91], v[144:147], v[130:133]
	s_waitcnt lgkmcnt(0)
	v_mfma_f32_16x16x32_bf16 v[88:91], v[88:91], v[148:151], v[92:95]
	v_mfma_f32_16x16x32_bf16 v[60:63], v[84:87], v[140:143], v[60:63]
	s_nop 4
	v_cvt_pk_bf16_f32 v92, v126, s0
	s_nop 0
	v_cvt_pk_bf16_f32 v88, v88, s0
	ds_write_b16 v101, v92 offset:13312
	v_mfma_f32_16x16x32_bf16 v[36:39], v[80:83], v[140:143], v[36:39]
	v_cvt_pk_bf16_f32 v92, v127, s0
	ds_write_b16 v101, v88 offset:13344
	v_cvt_pk_bf16_f32 v88, v89, s0
	v_mfma_f32_16x16x32_bf16 v[68:71], v[76:79], v[144:147], v[68:71]
	ds_write_b16 v101, v92 offset:13392
	v_cvt_pk_bf16_f32 v92, v128, s0
	ds_write_b16 v101, v88 offset:13424
	v_mfma_f32_16x16x32_bf16 v[56:59], v[72:75], v[144:147], v[56:59]
	v_cvt_pk_bf16_f32 v88, v90, s0
	ds_write_b16 v101, v92 offset:13472
	v_cvt_pk_bf16_f32 v92, v129, s0
	v_mfma_f32_16x16x32_bf16 v[60:63], v[76:79], v[148:151], v[60:63]
	ds_write_b16 v101, v88 offset:13504
	v_cvt_pk_bf16_f32 v88, v91, s0
	s_nop 1
	v_cvt_pk_bf16_f32 v76, v56, v57
	v_mfma_f32_16x16x32_bf16 v[36:39], v[72:75], v[148:151], v[36:39]
	v_cvt_pk_bf16_f32 v72, v68, v69
	v_cvt_pk_bf16_f32 v73, v70, v71
	v_cvt_pk_bf16_f32 v77, v58, v59
	ds_write_b16 v101, v92 offset:13552
	ds_write_b16 v101, v88 offset:13584
	v_cvt_pk_bf16_f32 v74, v60, v61
	v_cvt_pk_bf16_f32 v75, v62, v63
	ds_write2_b64 v99, v[72:73], v[76:77] offset1:4
	v_cvt_pk_bf16_f32 v76, v36, v37
	v_cvt_pk_bf16_f32 v77, v38, v39
	v_add_u32_e32 v72, 0x1000, v99
	ds_write2_b64 v72, v[74:75], v[76:77] offset0:32 offset1:36
	s_waitcnt lgkmcnt(0)
	s_waitcnt vmcnt(5)
	s_barrier
	ds_read_b128 v[74:77], v97 offset:13312
	v_lshl_add_u64 v[78:79], s[72:73], 0, v[106:107]
	v_lshl_add_u64 v[106:107], v[106:107], 0, s[12:13]
	s_waitcnt lgkmcnt(0)
	global_store_dwordx4 v[78:79], v[74:77], off
	s_waitcnt vmcnt(1)
	v_mov_b64_e32 v[92:93], v[16:17]
	v_mov_b64_e32 v[94:95], v[18:19]
	v_mov_b64_e32 v[88:89], v[20:21]
	v_mov_b64_e32 v[90:91], v[22:23]
	v_mov_b64_e32 v[120:121], v[104:105]
	v_mov_b64_e32 v[118:119], v[102:103]
	v_mov_b32_e32 v116, v100
	ds_read_b128 v[148:151], v204
	ds_read_b128 v[126:129], v204 offset:16384
	ds_read_b128 v[170:173], v205
	ds_read_b128 v[130:133], v205 offset:16384
	ds_read_b128 v[174:177], v206
	ds_read_b128 v[140:143], v206 offset:16384
	ds_read_b128 v[178:181], v207
	ds_read_b128 v[144:147], v207 offset:16384
	ds_read_b128 v[84:87], v210 offset:32768
	ds_read_b128 v[80:83], v210 offset:34816
	ds_read_b128 v[76:79], v211 offset:32768
	ds_read_b128 v[72:75], v211 offset:34816
	s_add_u32 m0, s36, 0x4800
	s_nop 0
	global_load_lds_dwordx4 v194, s[38:39]
	s_add_u32 m0, s36, 0x4c00
	s_nop 0
	global_load_lds_dwordx4 v195, s[38:39]
	s_add_u32 m0, s36, 0x8800
	s_nop 0
	global_load_lds_dwordx4 v196, s[38:39]
	s_add_u32 m0, s36, 0x8c00
	s_nop 0
	global_load_lds_dwordx4 v197, s[38:39]
	s_add_u32 m0, s36, 0xc800
	s_nop 0
	global_load_lds_dwordx4 v198, s[38:39]
	s_add_u32 m0, s36, 0xcc00
	s_nop 0
	global_load_lds_dwordx4 v199, s[38:39]
	s_add_u32 s38, s38, 0x4000
	s_addc_u32 s39, s39, 0
	v_lshl_add_u64 v[0:1], s[72:73], 0, v[110:111]
	s_mov_b32 s7, 0x23502000
	v_add_co_u32_e32 v0, vcc, s7, v0
	s_nop 1
	v_addc_co_u32_e32 v1, vcc, 0, v1, vcc
	global_load_dwordx4 v[16:19], v[0:1], off
	global_load_dwordx4 v[20:23], v[0:1], off offset:64
	v_lshl_add_u64 v[102:103], s[72:73], 0, v[108:109]
	s_mov_b32 s7, 0x1d504000
	v_add_co_u32_e32 v102, vcc, s7, v102
	s_add_u32 s8, s72, s1
	s_nop 0
	v_addc_co_u32_e32 v103, vcc, 0, v103, vcc
	s_addc_u32 s9, s73, s11
	global_load_dwordx2 v[104:105], v[102:103], off
	s_nop 0
	global_load_dwordx2 v[102:103], v[102:103], off offset:2048
	ds_read_b128 v[182:185], v124
	ds_read_b128 v[190:193], v124 offset:4352
	global_load_dword v100, v137, s[8:9]
	s_waitcnt lgkmcnt(1)
	v_mfma_f32_16x16x32_bf16 v[186:189], v[148:151], v[182:185], 0
	v_lshlrev_b32_e32 v134, 16, v120
	v_and_b32_e32 v135, 0xffff0000, v120
	v_lshlrev_b32_e32 v120, 16, v121
	v_mfma_f32_16x16x32_bf16 v[182:185], v[126:129], v[182:185], 0
	v_and_b32_e32 v121, 0xffff0000, v121
	v_pk_mul_f32 v[70:71], v[70:71], v[116:117] op_sel_hi:[1,0]
	v_pk_mul_f32 v[68:69], v[68:69], v[116:117] op_sel_hi:[1,0]
	s_waitcnt lgkmcnt(0)
	v_mfma_f32_16x16x32_bf16 v[148:151], v[148:151], v[190:193], 0
	v_mul_f32_e64 v58, v58, v116
	v_mul_f32_e64 v59, v59, v116
	v_pk_mul_f32 v[56:57], v[56:57], v[116:117] op_sel_hi:[1,0]
	v_pk_mul_f32 v[62:63], v[62:63], v[116:117] op_sel_hi:[1,0]
	v_mfma_f32_16x16x32_bf16 v[126:129], v[126:129], v[190:193], 0
	ds_read_b128 v[190:193], v124 offset:64
	v_pk_mul_f32 v[60:61], v[60:61], v[116:117] op_sel_hi:[1,0]
	v_pk_mul_f32 v[38:39], v[38:39], v[116:117] op_sel_hi:[1,0]
	s_waitcnt lgkmcnt(0)
	v_mfma_f32_16x16x32_bf16 v[186:189], v[170:173], v[190:193], v[186:189]
	v_mul_f32_e64 v36, v36, v116
	v_mul_f32_e64 v37, v37, v116
	s_add_i32 s6, s6, -1
	s_add_u32 s1, s1, 4
	v_mfma_f32_16x16x32_bf16 v[182:185], v[130:133], v[190:193], v[182:185]
	ds_read_b128 v[190:193], v124 offset:4416
	s_addc_u32 s11, s11, 0
	v_lshl_add_u64 v[108:109], v[108:109], 0, s[26:27]
	s_waitcnt lgkmcnt(0)
	v_mfma_f32_16x16x32_bf16 v[126:129], v[130:133], v[190:193], v[126:129]
	ds_read_b128 v[130:133], v124 offset:128
	v_lshl_add_u64 v[110:111], v[110:111], 0, s[14:15]
	v_lshl_add_u64 v[112:113], v[112:113], 0, s[26:27]
	v_mfma_f32_16x16x32_bf16 v[148:151], v[170:173], v[190:193], v[148:151]
	v_lshl_add_u64 v[114:115], v[114:115], 0, s[26:27]
	s_cmp_lg_u32 s6, 0
	s_waitcnt lgkmcnt(0)
	v_mfma_f32_16x16x32_bf16 v[170:173], v[174:177], v[130:133], v[186:189]
	v_mfma_f32_16x16x32_bf16 v[130:133], v[140:143], v[130:133], v[182:185]
	s_nop 2
	ds_read_b128 v[182:185], v124 offset:4480
	s_waitcnt lgkmcnt(0)
	v_mfma_f32_16x16x32_bf16 v[126:129], v[140:143], v[182:185], v[126:129]
	ds_read_b128 v[140:143], v124 offset:192
	s_waitcnt lgkmcnt(0)
	v_mfma_f32_16x16x32_bf16 v[170:173], v[178:181], v[140:143], v[170:173]
	v_mfma_f32_16x16x32_bf16 v[130:133], v[144:147], v[140:143], v[130:133]
	ds_read_b128 v[140:143], v124 offset:4544
	s_nop 5
	v_pk_add_f32 v[134:135], v[134:135], v[170:171] neg_lo:[0,1] neg_hi:[0,1]
	v_pk_add_f32 v[120:121], v[120:121], v[172:173] neg_lo:[0,1] neg_hi:[0,1]
	v_mfma_f32_16x16x32_bf16 v[148:151], v[174:177], v[182:185], v[148:151]
	v_cvt_pk_bf16_f32 v134, v134, v135
	v_cvt_pk_bf16_f32 v135, v120, v121
	v_lshlrev_b32_e32 v120, 16, v118
	s_waitcnt lgkmcnt(0)
	v_mfma_f32_16x16x32_bf16 v[148:151], v[178:181], v[140:143], v[148:151]
	v_and_b32_e32 v121, 0xffff0000, v118
	v_lshlrev_b32_e32 v118, 16, v119
	v_and_b32_e32 v119, 0xffff0000, v119
	ds_write_b64 v117, v[134:135] offset:8704
	v_mfma_f32_16x16x32_bf16 v[126:129], v[144:147], v[140:143], v[126:129]
	s_nop 2
	v_add_f32_e64 v120, v120, -v148
	v_add_f32_e64 v121, v121, -v149
	v_pk_add_f32 v[118:119], v[118:119], v[150:151] neg_lo:[0,1] neg_hi:[0,1]
	v_cvt_pk_bf16_f32 v120, v120, v121
	v_cvt_pk_bf16_f32 v121, v118, v119
	ds_write_b64 v117, v[120:121] offset:11008
	s_waitcnt lgkmcnt(0)
	s_barrier
	ds_read_b128 v[118:121], v122 offset:8704
	ds_read_b128 v[140:143], v123 offset:13056
	ds_read_b128 v[144:147], v122 offset:8768
	ds_read_b128 v[148:151], v123 offset:13120
	s_waitcnt lgkmcnt(3)
	v_mfma_f32_16x16x32_bf16 v[130:133], v[92:95], v[118:121], v[130:133]
	s_waitcnt lgkmcnt(2)
	v_mfma_f32_16x16x32_bf16 v[92:95], v[92:95], v[140:143], v[126:129]
	v_mfma_f32_16x16x32_bf16 v[68:71], v[84:87], v[118:121], v[68:71]
	v_mfma_f32_16x16x32_bf16 v[56:59], v[80:83], v[118:121], v[56:59]
	s_waitcnt lgkmcnt(1)
	v_mfma_f32_16x16x32_bf16 v[126:129], v[88:91], v[144:147], v[130:133]
	s_waitcnt lgkmcnt(0)
	v_mfma_f32_16x16x32_bf16 v[88:91], v[88:91], v[148:151], v[92:95]
	v_mfma_f32_16x16x32_bf16 v[60:63], v[84:87], v[140:143], v[60:63]
	s_nop 4
	v_cvt_pk_bf16_f32 v92, v126, s0
	s_nop 0
	v_cvt_pk_bf16_f32 v88, v88, s0
	ds_write_b16 v101, v92 offset:13312
	v_mfma_f32_16x16x32_bf16 v[36:39], v[80:83], v[140:143], v[36:39]
	v_cvt_pk_bf16_f32 v92, v127, s0
	ds_write_b16 v101, v88 offset:13344
	v_cvt_pk_bf16_f32 v88, v89, s0
	v_mfma_f32_16x16x32_bf16 v[68:71], v[76:79], v[144:147], v[68:71]
	ds_write_b16 v101, v92 offset:13392
	v_cvt_pk_bf16_f32 v92, v128, s0
	ds_write_b16 v101, v88 offset:13424
	v_mfma_f32_16x16x32_bf16 v[56:59], v[72:75], v[144:147], v[56:59]
	v_cvt_pk_bf16_f32 v88, v90, s0
	ds_write_b16 v101, v92 offset:13472
	v_cvt_pk_bf16_f32 v92, v129, s0
	v_mfma_f32_16x16x32_bf16 v[60:63], v[76:79], v[148:151], v[60:63]
	ds_write_b16 v101, v88 offset:13504
	v_cvt_pk_bf16_f32 v88, v91, s0
	s_nop 1
	v_cvt_pk_bf16_f32 v76, v56, v57
	v_mfma_f32_16x16x32_bf16 v[36:39], v[72:75], v[148:151], v[36:39]
	v_cvt_pk_bf16_f32 v72, v68, v69
	v_cvt_pk_bf16_f32 v73, v70, v71
	v_cvt_pk_bf16_f32 v77, v58, v59
	ds_write_b16 v101, v92 offset:13552
	ds_write_b16 v101, v88 offset:13584
	v_cvt_pk_bf16_f32 v74, v60, v61
	v_cvt_pk_bf16_f32 v75, v62, v63
	ds_write2_b64 v99, v[72:73], v[76:77] offset1:4
	v_cvt_pk_bf16_f32 v76, v36, v37
	v_cvt_pk_bf16_f32 v77, v38, v39
	v_add_u32_e32 v72, 0x1000, v99
	ds_write2_b64 v72, v[74:75], v[76:77] offset0:32 offset1:36
	s_waitcnt lgkmcnt(0)
	s_waitcnt vmcnt(5)
	s_barrier
	ds_read_b128 v[74:77], v97 offset:13312
	v_lshl_add_u64 v[78:79], s[72:73], 0, v[106:107]
	v_lshl_add_u64 v[106:107], v[106:107], 0, s[12:13]
	s_waitcnt lgkmcnt(0)
	global_store_dwordx4 v[78:79], v[74:77], off
	s_cbranch_scc1 .LBB0_469
	s_waitcnt vmcnt(1)
	v_mov_b64_e32 v[92:93], v[16:17]
	v_mov_b64_e32 v[94:95], v[18:19]
	v_mov_b64_e32 v[88:89], v[20:21]
	v_mov_b64_e32 v[90:91], v[22:23]
	v_mov_b64_e32 v[120:121], v[104:105]
	v_mov_b64_e32 v[118:119], v[102:103]
	v_mov_b32_e32 v116, v100
	ds_read_b128 v[148:151], v200
	ds_read_b128 v[126:129], v200 offset:16384
	ds_read_b128 v[170:173], v201
	ds_read_b128 v[130:133], v201 offset:16384
	ds_read_b128 v[174:177], v202
	ds_read_b128 v[140:143], v202 offset:16384
	ds_read_b128 v[178:181], v203
	ds_read_b128 v[144:147], v203 offset:16384
	ds_read_b128 v[84:87], v208 offset:32768
	ds_read_b128 v[80:83], v208 offset:34816
	ds_read_b128 v[76:79], v209 offset:32768
	ds_read_b128 v[72:75], v209 offset:34816
	s_add_u32 m0, s36, 0x16800
	s_nop 0
	global_load_lds_dwordx4 v194, s[38:39]
	s_add_u32 m0, s36, 0x16c00
	s_nop 0
	global_load_lds_dwordx4 v195, s[38:39]
	s_add_u32 m0, s36, 0x1a800
	s_nop 0
	global_load_lds_dwordx4 v196, s[38:39]
	s_add_u32 m0, s36, 0x1ac00
	s_nop 0
	global_load_lds_dwordx4 v197, s[38:39]
	s_add_u32 m0, s36, 0x1e800
	s_nop 0
	global_load_lds_dwordx4 v198, s[38:39]
	s_add_u32 m0, s36, 0x1ec00
	s_nop 0
	global_load_lds_dwordx4 v199, s[38:39]
	s_add_u32 s38, s38, 0x4000
	s_addc_u32 s39, s39, 0
	v_lshl_add_u64 v[0:1], s[72:73], 0, v[110:111]
	s_mov_b32 s7, 0x23502000
	v_add_co_u32_e32 v0, vcc, s7, v0
	s_nop 1
	v_addc_co_u32_e32 v1, vcc, 0, v1, vcc
	global_load_dwordx4 v[16:19], v[0:1], off
	global_load_dwordx4 v[20:23], v[0:1], off offset:64
	v_lshl_add_u64 v[102:103], s[72:73], 0, v[108:109]
	s_mov_b32 s7, 0x1d504000
	v_add_co_u32_e32 v102, vcc, s7, v102
	s_add_u32 s8, s72, s1
	s_nop 0
	v_addc_co_u32_e32 v103, vcc, 0, v103, vcc
	s_addc_u32 s9, s73, s11
	global_load_dwordx2 v[104:105], v[102:103], off
	s_nop 0
	global_load_dwordx2 v[102:103], v[102:103], off offset:2048
	ds_read_b128 v[182:185], v124
	ds_read_b128 v[190:193], v124 offset:4352
	global_load_dword v100, v137, s[8:9]
	s_waitcnt lgkmcnt(1)
	v_mfma_f32_16x16x32_bf16 v[186:189], v[148:151], v[182:185], 0
	v_lshlrev_b32_e32 v134, 16, v120
	v_and_b32_e32 v135, 0xffff0000, v120
	v_lshlrev_b32_e32 v120, 16, v121
	v_mfma_f32_16x16x32_bf16 v[182:185], v[126:129], v[182:185], 0
	v_and_b32_e32 v121, 0xffff0000, v121
	v_pk_mul_f32 v[70:71], v[70:71], v[116:117] op_sel_hi:[1,0]
	v_pk_mul_f32 v[68:69], v[68:69], v[116:117] op_sel_hi:[1,0]
	s_waitcnt lgkmcnt(0)
	v_mfma_f32_16x16x32_bf16 v[148:151], v[148:151], v[190:193], 0
	v_mul_f32_e64 v58, v58, v116
	v_mul_f32_e64 v59, v59, v116
	v_pk_mul_f32 v[56:57], v[56:57], v[116:117] op_sel_hi:[1,0]
	v_pk_mul_f32 v[62:63], v[62:63], v[116:117] op_sel_hi:[1,0]
	v_mfma_f32_16x16x32_bf16 v[126:129], v[126:129], v[190:193], 0
	ds_read_b128 v[190:193], v124 offset:64
	v_pk_mul_f32 v[60:61], v[60:61], v[116:117] op_sel_hi:[1,0]
	v_pk_mul_f32 v[38:39], v[38:39], v[116:117] op_sel_hi:[1,0]
	s_waitcnt lgkmcnt(0)
	v_mfma_f32_16x16x32_bf16 v[186:189], v[170:173], v[190:193], v[186:189]
	v_mul_f32_e64 v36, v36, v116
	v_mul_f32_e64 v37, v37, v116
	s_add_i32 s6, s6, -1
	s_add_u32 s1, s1, 4
	v_mfma_f32_16x16x32_bf16 v[182:185], v[130:133], v[190:193], v[182:185]
	ds_read_b128 v[190:193], v124 offset:4416
	s_addc_u32 s11, s11, 0
	v_lshl_add_u64 v[108:109], v[108:109], 0, s[26:27]
	s_waitcnt lgkmcnt(0)
	v_mfma_f32_16x16x32_bf16 v[126:129], v[130:133], v[190:193], v[126:129]
	ds_read_b128 v[130:133], v124 offset:128
	v_lshl_add_u64 v[110:111], v[110:111], 0, s[14:15]
	v_lshl_add_u64 v[112:113], v[112:113], 0, s[26:27]
	v_mfma_f32_16x16x32_bf16 v[148:151], v[170:173], v[190:193], v[148:151]
	v_lshl_add_u64 v[114:115], v[114:115], 0, s[26:27]
	s_cmp_lg_u32 s6, 0
	s_waitcnt lgkmcnt(0)
	v_mfma_f32_16x16x32_bf16 v[170:173], v[174:177], v[130:133], v[186:189]
	v_mfma_f32_16x16x32_bf16 v[130:133], v[140:143], v[130:133], v[182:185]
	s_nop 2
	ds_read_b128 v[182:185], v124 offset:4480
	s_waitcnt lgkmcnt(0)
	v_mfma_f32_16x16x32_bf16 v[126:129], v[140:143], v[182:185], v[126:129]
	ds_read_b128 v[140:143], v124 offset:192
	s_waitcnt lgkmcnt(0)
	v_mfma_f32_16x16x32_bf16 v[170:173], v[178:181], v[140:143], v[170:173]
	v_mfma_f32_16x16x32_bf16 v[130:133], v[144:147], v[140:143], v[130:133]
	ds_read_b128 v[140:143], v124 offset:4544
	s_nop 5
	v_pk_add_f32 v[134:135], v[134:135], v[170:171] neg_lo:[0,1] neg_hi:[0,1]
	v_pk_add_f32 v[120:121], v[120:121], v[172:173] neg_lo:[0,1] neg_hi:[0,1]
	v_mfma_f32_16x16x32_bf16 v[148:151], v[174:177], v[182:185], v[148:151]
	v_cvt_pk_bf16_f32 v134, v134, v135
	v_cvt_pk_bf16_f32 v135, v120, v121
	v_lshlrev_b32_e32 v120, 16, v118
	s_waitcnt lgkmcnt(0)
	v_mfma_f32_16x16x32_bf16 v[148:151], v[178:181], v[140:143], v[148:151]
	v_and_b32_e32 v121, 0xffff0000, v118
	v_lshlrev_b32_e32 v118, 16, v119
	v_and_b32_e32 v119, 0xffff0000, v119
	ds_write_b64 v117, v[134:135] offset:8704
	v_mfma_f32_16x16x32_bf16 v[126:129], v[144:147], v[140:143], v[126:129]
	s_nop 2
	v_add_f32_e64 v120, v120, -v148
	v_add_f32_e64 v121, v121, -v149
	v_pk_add_f32 v[118:119], v[118:119], v[150:151] neg_lo:[0,1] neg_hi:[0,1]
	v_cvt_pk_bf16_f32 v120, v120, v121
	v_cvt_pk_bf16_f32 v121, v118, v119
	ds_write_b64 v117, v[120:121] offset:11008
	s_waitcnt lgkmcnt(0)
	s_barrier
	ds_read_b128 v[118:121], v122 offset:8704
	ds_read_b128 v[140:143], v123 offset:13056
	ds_read_b128 v[144:147], v122 offset:8768
	ds_read_b128 v[148:151], v123 offset:13120
	s_waitcnt lgkmcnt(3)
	v_mfma_f32_16x16x32_bf16 v[130:133], v[92:95], v[118:121], v[130:133]
	s_waitcnt lgkmcnt(2)
	v_mfma_f32_16x16x32_bf16 v[92:95], v[92:95], v[140:143], v[126:129]
	v_mfma_f32_16x16x32_bf16 v[68:71], v[84:87], v[118:121], v[68:71]
	v_mfma_f32_16x16x32_bf16 v[56:59], v[80:83], v[118:121], v[56:59]
	s_waitcnt lgkmcnt(1)
	v_mfma_f32_16x16x32_bf16 v[126:129], v[88:91], v[144:147], v[130:133]
	s_waitcnt lgkmcnt(0)
	v_mfma_f32_16x16x32_bf16 v[88:91], v[88:91], v[148:151], v[92:95]
	v_mfma_f32_16x16x32_bf16 v[60:63], v[84:87], v[140:143], v[60:63]
	s_nop 4
	v_cvt_pk_bf16_f32 v92, v126, s0
	s_nop 0
	v_cvt_pk_bf16_f32 v88, v88, s0
	ds_write_b16 v101, v92 offset:13312
	v_mfma_f32_16x16x32_bf16 v[36:39], v[80:83], v[140:143], v[36:39]
	v_cvt_pk_bf16_f32 v92, v127, s0
	ds_write_b16 v101, v88 offset:13344
	v_cvt_pk_bf16_f32 v88, v89, s0
	v_mfma_f32_16x16x32_bf16 v[68:71], v[76:79], v[144:147], v[68:71]
	ds_write_b16 v101, v92 offset:13392
	v_cvt_pk_bf16_f32 v92, v128, s0
	ds_write_b16 v101, v88 offset:13424
	v_mfma_f32_16x16x32_bf16 v[56:59], v[72:75], v[144:147], v[56:59]
	v_cvt_pk_bf16_f32 v88, v90, s0
	ds_write_b16 v101, v92 offset:13472
	v_cvt_pk_bf16_f32 v92, v129, s0
	v_mfma_f32_16x16x32_bf16 v[60:63], v[76:79], v[148:151], v[60:63]
	ds_write_b16 v101, v88 offset:13504
	v_cvt_pk_bf16_f32 v88, v91, s0
	s_nop 1
	v_cvt_pk_bf16_f32 v76, v56, v57
	v_mfma_f32_16x16x32_bf16 v[36:39], v[72:75], v[148:151], v[36:39]
	v_cvt_pk_bf16_f32 v72, v68, v69
	v_cvt_pk_bf16_f32 v73, v70, v71
	v_cvt_pk_bf16_f32 v77, v58, v59
	ds_write_b16 v101, v92 offset:13552
	ds_write_b16 v101, v88 offset:13584
	v_cvt_pk_bf16_f32 v74, v60, v61
	v_cvt_pk_bf16_f32 v75, v62, v63
	ds_write2_b64 v99, v[72:73], v[76:77] offset1:4
	v_cvt_pk_bf16_f32 v76, v36, v37
	v_cvt_pk_bf16_f32 v77, v38, v39
	v_add_u32_e32 v72, 0x1000, v99
	ds_write2_b64 v72, v[74:75], v[76:77] offset0:32 offset1:36
	s_waitcnt lgkmcnt(0)
	s_waitcnt vmcnt(5)
	s_barrier
	ds_read_b128 v[74:77], v97 offset:13312
	v_lshl_add_u64 v[78:79], s[72:73], 0, v[106:107]
	v_lshl_add_u64 v[106:107], v[106:107], 0, s[12:13]
	s_waitcnt lgkmcnt(0)
	global_store_dwordx4 v[78:79], v[74:77], off
	ds_read_b128 v[52:55], v204
	ds_read_b128 v[64:67], v204 offset:16384
	ds_read_b128 v[44:47], v205
	ds_read_b128 v[48:51], v205 offset:16384
	ds_read_b128 v[32:35], v206
	ds_read_b128 v[40:43], v206 offset:16384
	ds_read_b128 v[24:27], v207
	ds_read_b128 v[28:31], v207 offset:16384
	ds_read_b128 v[12:15], v210 offset:32768
	ds_read_b128 v[8:11], v210 offset:34816
	ds_read_b128 v[4:7], v211 offset:32768
	ds_read_b128 v[0:3], v211 offset:34816
	s_waitcnt lgkmcnt(0)
	ds_read_b128 v[74:77], v124
	ds_read_b128 v[82:85], v124 offset:4352
	s_waitcnt vmcnt(1)
	v_pk_mul_f32 v[38:39], v[100:101], v[38:39] op_sel_hi:[0,1]
	v_pk_mul_f32 v[36:37], v[100:101], v[36:37] op_sel_hi:[0,1]
	s_mov_b32 s1, s52
	s_waitcnt lgkmcnt(1)
	v_mfma_f32_16x16x32_bf16 v[78:81], v[52:55], v[74:77], 0
	v_mfma_f32_16x16x32_bf16 v[74:77], v[64:67], v[74:77], 0
	s_waitcnt lgkmcnt(0)
	v_mfma_f32_16x16x32_bf16 v[52:55], v[52:55], v[82:85], 0
	v_mfma_f32_16x16x32_bf16 v[64:67], v[64:67], v[82:85], 0
	ds_read_b128 v[82:85], v124 offset:64
	s_waitcnt lgkmcnt(0)
	v_mfma_f32_16x16x32_bf16 v[78:81], v[44:47], v[82:85], v[78:81]
	v_mfma_f32_16x16x32_bf16 v[74:77], v[48:51], v[82:85], v[74:77]
	ds_read_b128 v[82:85], v124 offset:4416
	s_waitcnt lgkmcnt(0)
	v_mfma_f32_16x16x32_bf16 v[44:47], v[44:47], v[82:85], v[52:55]
	s_nop 2
	ds_read_b128 v[52:55], v124 offset:128
	v_mfma_f32_16x16x32_bf16 v[48:51], v[48:51], v[82:85], v[64:67]
	s_waitcnt lgkmcnt(0)
	v_mfma_f32_16x16x32_bf16 v[64:67], v[32:35], v[52:55], v[78:81]
	v_mfma_f32_16x16x32_bf16 v[52:55], v[40:43], v[52:55], v[74:77]
	s_nop 2
	ds_read_b128 v[74:77], v124 offset:4480
	s_waitcnt lgkmcnt(0)
	v_mfma_f32_16x16x32_bf16 v[32:35], v[32:35], v[74:77], v[44:47]
	s_nop 2
	ds_read_b128 v[44:47], v124 offset:192
	v_mfma_f32_16x16x32_bf16 v[40:43], v[40:43], v[74:77], v[48:51]
	s_waitcnt lgkmcnt(0)
	v_mfma_f32_16x16x32_bf16 v[48:51], v[24:27], v[44:47], v[64:67]
	v_mfma_f32_16x16x32_bf16 v[44:47], v[28:31], v[44:47], v[52:55]
	s_nop 2
	ds_read_b128 v[52:55], v124 offset:4544
	s_waitcnt lgkmcnt(0)
	v_mfma_f32_16x16x32_bf16 v[24:27], v[24:27], v[52:55], v[32:35]
	s_nop 2
	v_lshlrev_b32_e32 v32, 16, v104
	v_and_b32_e32 v33, 0xffff0000, v104
	v_lshlrev_b32_e32 v34, 16, v105
	v_and_b32_e32 v35, 0xffff0000, v105
	v_pk_add_f32 v[32:33], v[32:33], v[48:49] neg_lo:[0,1] neg_hi:[0,1]
	v_pk_add_f32 v[34:35], v[34:35], v[50:51] neg_lo:[0,1] neg_hi:[0,1]
	v_cvt_pk_bf16_f32 v32, v32, v33
	v_cvt_pk_bf16_f32 v33, v34, v35
	ds_write_b64 v117, v[32:33] offset:8704
	v_lshlrev_b32_e32 v32, 16, v102
	v_and_b32_e32 v33, 0xffff0000, v102
	v_pk_add_f32 v[24:25], v[32:33], v[24:25] neg_lo:[0,1] neg_hi:[0,1]
	v_lshlrev_b32_e32 v32, 16, v103
	v_and_b32_e32 v33, 0xffff0000, v103
	v_pk_add_f32 v[26:27], v[32:33], v[26:27] neg_lo:[0,1] neg_hi:[0,1]
	v_cvt_pk_bf16_f32 v24, v24, v25
	v_cvt_pk_bf16_f32 v25, v26, v27
	ds_write_b64 v117, v[24:25] offset:11008
	v_mfma_f32_16x16x32_bf16 v[28:31], v[28:31], v[52:55], v[40:43]
	s_waitcnt lgkmcnt(0)
	s_barrier
	ds_read_b128 v[24:27], v122 offset:8704
	ds_read_b128 v[32:35], v123 offset:13056
	ds_read_b128 v[40:43], v122 offset:8768
	ds_read_b128 v[48:51], v123 offset:13120
	s_waitcnt lgkmcnt(3)
	v_mfma_f32_16x16x32_bf16 v[44:47], v[16:19], v[24:27], v[44:47]
	s_waitcnt lgkmcnt(2)
	v_mfma_f32_16x16x32_bf16 v[16:19], v[16:19], v[32:35], v[28:31]
	s_waitcnt lgkmcnt(1)
	v_mfma_f32_16x16x32_bf16 v[28:31], v[20:23], v[40:43], v[44:47]
	s_waitcnt lgkmcnt(0)
	v_mfma_f32_16x16x32_bf16 v[16:19], v[20:23], v[48:51], v[16:19]
	v_mul_f32_e64 v22, v100, v62
	v_mul_f32_e64 v23, v100, v63
	s_nop 3
	v_cvt_pk_bf16_f32 v20, v28, s0
	ds_write_b16 v101, v20 offset:13312
	v_cvt_pk_bf16_f32 v20, v29, s0
	ds_write_b16 v101, v20 offset:13392
	v_cvt_pk_bf16_f32 v16, v16, s0
	ds_write_b16 v101, v16 offset:13344
	v_cvt_pk_bf16_f32 v16, v17, s0
	v_cvt_pk_bf16_f32 v20, v30, s0
	ds_write_b16 v101, v16 offset:13424
	v_cvt_pk_bf16_f32 v16, v18, s0
	ds_write_b16 v101, v20 offset:13472
	v_cvt_pk_bf16_f32 v20, v31, s0
	ds_write_b16 v101, v16 offset:13504
	v_cvt_pk_bf16_f32 v16, v19, s0
	ds_write_b16 v101, v20 offset:13552
	ds_write_b16 v101, v16 offset:13584
	v_pk_mul_f32 v[18:19], v[100:101], v[70:71] op_sel_hi:[0,1]
	v_pk_mul_f32 v[16:17], v[100:101], v[68:69] op_sel_hi:[0,1]
	v_pk_mul_f32 v[20:21], v[100:101], v[60:61] op_sel_hi:[0,1]
	v_pk_mul_f32 v[30:31], v[100:101], v[58:59] op_sel_hi:[0,1]
	v_pk_mul_f32 v[28:29], v[100:101], v[56:57] op_sel_hi:[0,1]
	v_mfma_f32_16x16x32_bf16 v[16:19], v[12:15], v[24:27], v[16:19]
	v_mfma_f32_16x16x32_bf16 v[12:15], v[12:15], v[32:35], v[20:23]
	v_mfma_f32_16x16x32_bf16 v[20:23], v[8:11], v[24:27], v[28:31]
	v_mfma_f32_16x16x32_bf16 v[8:11], v[8:11], v[32:35], v[36:39]
	v_mfma_f32_16x16x32_bf16 v[16:19], v[4:7], v[40:43], v[16:19]
	v_mfma_f32_16x16x32_bf16 v[4:7], v[4:7], v[48:51], v[12:15]
	v_mfma_f32_16x16x32_bf16 v[12:15], v[0:3], v[40:43], v[20:23]
	v_mfma_f32_16x16x32_bf16 v[0:3], v[0:3], v[48:51], v[8:11]
	s_nop 5
	v_cvt_pk_bf16_f32 v4, v4, v5
	v_cvt_pk_bf16_f32 v5, v6, v7
	v_cvt_pk_bf16_f32 v6, v12, v13
	v_cvt_pk_bf16_f32 v8, v16, v17
	v_cvt_pk_bf16_f32 v9, v18, v19
	v_cvt_pk_bf16_f32 v7, v14, v15
	v_cvt_pk_bf16_f32 v0, v0, v1
	v_cvt_pk_bf16_f32 v1, v2, v3
	ds_write2_b64 v99, v[8:9], v[6:7] offset1:4
	ds_write2_b64 v72, v[4:5], v[0:1] offset0:32 offset1:36
	s_waitcnt lgkmcnt(0)
	s_barrier
	v_lshl_or_b32 v4, v98, 11, s4
	v_mov_b32_e32 v5, s5
	v_readlane_b32 s4, v254, 36
	ds_read_b128 v[0:3], v97 offset:13312
	v_readlane_b32 s5, v254, 37
	v_mov_b32_e32 v97, v137
	s_nop 0
	v_lshl_add_u64 v[4:5], s[4:5], 0, v[4:5]
	v_lshl_add_u64 v[4:5], v[4:5], 0, s[0:1]
	s_lshl_b32 s0, s10, 6
	v_lshl_add_u64 v[4:5], v[4:5], 0, s[0:1]
	v_lshl_add_u64 v[4:5], v[4:5], 0, v[96:97]
	s_waitcnt lgkmcnt(0)
	global_store_dwordx4 v[4:5], v[0:3], off

.LBB0_666:
	v_readlane_b32 s4, v253, 0
	s_cmpk_lt_i32 s4, 0x80
	s_cbranch_scc1 .Lconv_ret3
	s_mov_b64 s[64:65], s[0:1]
	v_lshrrev_b32_e32 v0, 8, v154
	v_mul_u32_u24_e32 v122, 0x12000, v0
	v_mov_b32_e32 v1, v154
	s_nop 0
	v_readfirstlane_b32 s5, v1
	v_writelane_b32 v254, s4, 62
	s_lshl_b32 s6, s4, 1
	v_writelane_b32 v255, s6, 0
	v_writelane_b32 v254, s5, 63
	s_ashr_i32 s5, s5, 8
	s_add_i32 s6, s5, s6
	v_writelane_b32 v255, s5, 1
	v_writelane_b32 v254, s6, 61
	s_mov_b32 s92, 0xc0
	s_mov_b32 s93, 3
	s_branch .Lconv_entry
